# P0a modulation GEMV: silu staging issues its 17 row loads up front instead of 17 dependent load-wait iterations
# baseline (speedup 1.0000x reference)
.LBB0_41:
	s_or_b64 exec, exec, s[12:13]
	s_cmpk_gt_i32 s2, 0xbf
	s_barrier
	s_cbranch_scc1 .LBB0_55
	s_movk_i32 s0, 0x2100
	v_cmp_gt_i32_e32 vcc, s0, v1
	s_and_saveexec_b64 s[8:9], vcc
	s_cbranch_execz .LBB0_49
	s_load_dwordx2 s[4:5], s[78:79], 0x8
	s_load_dwordx2 s[12:13], s[78:79], 0x18
	v_lshlrev_b32_e32 v22, 4, v224
	v_lshrrev_b32_e32 v55, 8, v224
	v_and_b32_e32 v54, 0xff, v224
	v_lshlrev_b32_e32 v54, 4, v54
	v_mul_u32_u24_e32 v55, 0x1010, v55
	v_add_u32_e32 v32, v54, v55
	v_add_u32_e32 v33, 0x10100, v32
	v_add_u32_e32 v35, 0x20200, v32
	s_waitcnt lgkmcnt(0)
	global_load_dwordx4 v[18:21], v22, s[4:5]
	s_add_u32 s4, s4, 0x2000
	s_addc_u32 s5, s5, 0
	global_load_dwordx4 v[24:27], v22, s[4:5]
	s_add_u32 s4, s4, 0x2000
	s_addc_u32 s5, s5, 0
	global_load_dwordx4 v[28:31], v22, s[4:5]
	s_add_u32 s4, s4, 0x2000
	s_addc_u32 s5, s5, 0
	global_load_dwordx4 v[36:39], v22, s[4:5]
	s_add_u32 s4, s4, 0x2000
	s_addc_u32 s5, s5, 0
	global_load_dwordx4 v[40:43], v22, s[4:5]
	s_add_u32 s4, s4, 0x2000
	s_addc_u32 s5, s5, 0
	global_load_dwordx4 v[44:47], v22, s[4:5]
	s_add_u32 s4, s4, 0x2000
	s_addc_u32 s5, s5, 0
	global_load_dwordx4 v[50:53], v22, s[4:5]
	s_add_u32 s4, s4, 0x2000
	s_addc_u32 s5, s5, 0
	global_load_dwordx4 v[124:127], v22, s[4:5]
	s_add_u32 s4, s4, 0x2000
	s_addc_u32 s5, s5, 0
	global_load_dwordx4 v[128:131], v22, s[4:5]
	s_add_u32 s4, s4, 0x2000
	s_addc_u32 s5, s5, 0
	global_load_dwordx4 v[132:135], v22, s[4:5]
	s_add_u32 s4, s4, 0x2000
	s_addc_u32 s5, s5, 0
	global_load_dwordx4 v[136:139], v22, s[4:5]
	s_add_u32 s4, s4, 0x2000
	s_addc_u32 s5, s5, 0
	global_load_dwordx4 v[148:151], v22, s[4:5]
	s_add_u32 s4, s4, 0x2000
	s_addc_u32 s5, s5, 0
	global_load_dwordx4 v[152:155], v22, s[4:5]
	s_add_u32 s4, s4, 0x2000
	s_addc_u32 s5, s5, 0
	global_load_dwordx4 v[164:167], v22, s[4:5]
	s_add_u32 s4, s4, 0x2000
	s_addc_u32 s5, s5, 0
	global_load_dwordx4 v[168:171], v22, s[4:5]
	s_add_u32 s4, s4, 0x2000
	s_addc_u32 s5, s5, 0
	global_load_dwordx4 v[176:179], v22, s[4:5]
	s_add_u32 s4, s4, 0x2000
	s_addc_u32 s5, s5, 0
	global_load_dwordx4 v[180:183], v54, s[12:13]
	s_waitcnt vmcnt(16)
	v_mul_f32_e32 v56, 0xbfb8aa3b, v18
	v_mul_f32_e32 v72, 0xbfb8aa3b, v19
	v_mul_f32_e32 v98, 0xbfb8aa3b, v20
	v_mul_f32_e32 v100, 0xbfb8aa3b, v21
	v_exp_f32_e32 v56, v56
	v_exp_f32_e32 v72, v72
	v_exp_f32_e32 v98, v98
	v_exp_f32_e32 v100, v100
	s_nop 0
	v_add_f32_e32 v56, 1.0, v56
	v_add_f32_e32 v72, 1.0, v72
	v_add_f32_e32 v98, 1.0, v98
	v_add_f32_e32 v100, 1.0, v100
	v_rcp_f32_e32 v56, v56
	v_rcp_f32_e32 v72, v72
	v_rcp_f32_e32 v98, v98
	v_rcp_f32_e32 v100, v100
	s_nop 0
	v_mul_f32_e32 v18, v18, v56
	v_mul_f32_e32 v19, v19, v72
	v_mul_f32_e32 v20, v20, v98
	v_mul_f32_e32 v21, v21, v100
	ds_write_b128 v32, v[18:21]
	s_waitcnt vmcnt(15)
	v_mul_f32_e32 v56, 0xbfb8aa3b, v24
	v_mul_f32_e32 v72, 0xbfb8aa3b, v25
	v_mul_f32_e32 v98, 0xbfb8aa3b, v26
	v_mul_f32_e32 v100, 0xbfb8aa3b, v27
	v_exp_f32_e32 v56, v56
	v_exp_f32_e32 v72, v72
	v_exp_f32_e32 v98, v98
	v_exp_f32_e32 v100, v100
	s_nop 0
	v_add_f32_e32 v56, 1.0, v56
	v_add_f32_e32 v72, 1.0, v72
	v_add_f32_e32 v98, 1.0, v98
	v_add_f32_e32 v100, 1.0, v100
	v_rcp_f32_e32 v56, v56
	v_rcp_f32_e32 v72, v72
	v_rcp_f32_e32 v98, v98
	v_rcp_f32_e32 v100, v100
	s_nop 0
	v_mul_f32_e32 v24, v24, v56
	v_mul_f32_e32 v25, v25, v72
	v_mul_f32_e32 v26, v26, v98
	v_mul_f32_e32 v27, v27, v100
	ds_write_b128 v32, v[24:27] offset:8224
	s_waitcnt vmcnt(14)
	v_mul_f32_e32 v56, 0xbfb8aa3b, v28
	v_mul_f32_e32 v72, 0xbfb8aa3b, v29
	v_mul_f32_e32 v98, 0xbfb8aa3b, v30
	v_mul_f32_e32 v100, 0xbfb8aa3b, v31
	v_exp_f32_e32 v56, v56
	v_exp_f32_e32 v72, v72
	v_exp_f32_e32 v98, v98
	v_exp_f32_e32 v100, v100
	s_nop 0
	v_add_f32_e32 v56, 1.0, v56
	v_add_f32_e32 v72, 1.0, v72
	v_add_f32_e32 v98, 1.0, v98
	v_add_f32_e32 v100, 1.0, v100
	v_rcp_f32_e32 v56, v56
	v_rcp_f32_e32 v72, v72
	v_rcp_f32_e32 v98, v98
	v_rcp_f32_e32 v100, v100
	s_nop 0
	v_mul_f32_e32 v28, v28, v56
	v_mul_f32_e32 v29, v29, v72
	v_mul_f32_e32 v30, v30, v98
	v_mul_f32_e32 v31, v31, v100
	ds_write_b128 v32, v[28:31] offset:16448
	s_waitcnt vmcnt(13)
	v_mul_f32_e32 v56, 0xbfb8aa3b, v36
	v_mul_f32_e32 v72, 0xbfb8aa3b, v37
	v_mul_f32_e32 v98, 0xbfb8aa3b, v38
	v_mul_f32_e32 v100, 0xbfb8aa3b, v39
	v_exp_f32_e32 v56, v56
	v_exp_f32_e32 v72, v72
	v_exp_f32_e32 v98, v98
	v_exp_f32_e32 v100, v100
	s_nop 0
	v_add_f32_e32 v56, 1.0, v56
	v_add_f32_e32 v72, 1.0, v72
	v_add_f32_e32 v98, 1.0, v98
	v_add_f32_e32 v100, 1.0, v100
	v_rcp_f32_e32 v56, v56
	v_rcp_f32_e32 v72, v72
	v_rcp_f32_e32 v98, v98
	v_rcp_f32_e32 v100, v100
	s_nop 0
	v_mul_f32_e32 v36, v36, v56
	v_mul_f32_e32 v37, v37, v72
	v_mul_f32_e32 v38, v38, v98
	v_mul_f32_e32 v39, v39, v100
	ds_write_b128 v32, v[36:39] offset:24672
	s_waitcnt vmcnt(12)
	v_mul_f32_e32 v56, 0xbfb8aa3b, v40
	v_mul_f32_e32 v72, 0xbfb8aa3b, v41
	v_mul_f32_e32 v98, 0xbfb8aa3b, v42
	v_mul_f32_e32 v100, 0xbfb8aa3b, v43
	v_exp_f32_e32 v56, v56
	v_exp_f32_e32 v72, v72
	v_exp_f32_e32 v98, v98
	v_exp_f32_e32 v100, v100
	s_nop 0
	v_add_f32_e32 v56, 1.0, v56
	v_add_f32_e32 v72, 1.0, v72
	v_add_f32_e32 v98, 1.0, v98
	v_add_f32_e32 v100, 1.0, v100
	v_rcp_f32_e32 v56, v56
	v_rcp_f32_e32 v72, v72
	v_rcp_f32_e32 v98, v98
	v_rcp_f32_e32 v100, v100
	s_nop 0
	v_mul_f32_e32 v40, v40, v56
	v_mul_f32_e32 v41, v41, v72
	v_mul_f32_e32 v42, v42, v98
	v_mul_f32_e32 v43, v43, v100
	ds_write_b128 v32, v[40:43] offset:32896
	s_waitcnt vmcnt(11)
	v_mul_f32_e32 v56, 0xbfb8aa3b, v44
	v_mul_f32_e32 v72, 0xbfb8aa3b, v45
	v_mul_f32_e32 v98, 0xbfb8aa3b, v46
	v_mul_f32_e32 v100, 0xbfb8aa3b, v47
	v_exp_f32_e32 v56, v56
	v_exp_f32_e32 v72, v72
	v_exp_f32_e32 v98, v98
	v_exp_f32_e32 v100, v100
	s_nop 0
	v_add_f32_e32 v56, 1.0, v56
	v_add_f32_e32 v72, 1.0, v72
	v_add_f32_e32 v98, 1.0, v98
	v_add_f32_e32 v100, 1.0, v100
	v_rcp_f32_e32 v56, v56
	v_rcp_f32_e32 v72, v72
	v_rcp_f32_e32 v98, v98
	v_rcp_f32_e32 v100, v100
	s_nop 0
	v_mul_f32_e32 v44, v44, v56
	v_mul_f32_e32 v45, v45, v72
	v_mul_f32_e32 v46, v46, v98
	v_mul_f32_e32 v47, v47, v100
	ds_write_b128 v32, v[44:47] offset:41120
	s_waitcnt vmcnt(10)
	v_mul_f32_e32 v56, 0xbfb8aa3b, v50
	v_mul_f32_e32 v72, 0xbfb8aa3b, v51
	v_mul_f32_e32 v98, 0xbfb8aa3b, v52
	v_mul_f32_e32 v100, 0xbfb8aa3b, v53
	v_exp_f32_e32 v56, v56
	v_exp_f32_e32 v72, v72
	v_exp_f32_e32 v98, v98
	v_exp_f32_e32 v100, v100
	s_nop 0
	v_add_f32_e32 v56, 1.0, v56
	v_add_f32_e32 v72, 1.0, v72
	v_add_f32_e32 v98, 1.0, v98
	v_add_f32_e32 v100, 1.0, v100
	v_rcp_f32_e32 v56, v56
	v_rcp_f32_e32 v72, v72
	v_rcp_f32_e32 v98, v98
	v_rcp_f32_e32 v100, v100
	s_nop 0
	v_mul_f32_e32 v50, v50, v56
	v_mul_f32_e32 v51, v51, v72
	v_mul_f32_e32 v52, v52, v98
	v_mul_f32_e32 v53, v53, v100
	ds_write_b128 v32, v[50:53] offset:49344
	s_waitcnt vmcnt(9)
	v_mul_f32_e32 v56, 0xbfb8aa3b, v124
	v_mul_f32_e32 v72, 0xbfb8aa3b, v125
	v_mul_f32_e32 v98, 0xbfb8aa3b, v126
	v_mul_f32_e32 v100, 0xbfb8aa3b, v127
	v_exp_f32_e32 v56, v56
	v_exp_f32_e32 v72, v72
	v_exp_f32_e32 v98, v98
	v_exp_f32_e32 v100, v100
	s_nop 0
	v_add_f32_e32 v56, 1.0, v56
	v_add_f32_e32 v72, 1.0, v72
	v_add_f32_e32 v98, 1.0, v98
	v_add_f32_e32 v100, 1.0, v100
	v_rcp_f32_e32 v56, v56
	v_rcp_f32_e32 v72, v72
	v_rcp_f32_e32 v98, v98
	v_rcp_f32_e32 v100, v100
	s_nop 0
	v_mul_f32_e32 v124, v124, v56
	v_mul_f32_e32 v125, v125, v72
	v_mul_f32_e32 v126, v126, v98
	v_mul_f32_e32 v127, v127, v100
	ds_write_b128 v32, v[124:127] offset:57568
	s_waitcnt vmcnt(8)
	v_mul_f32_e32 v56, 0xbfb8aa3b, v128
	v_mul_f32_e32 v72, 0xbfb8aa3b, v129
	v_mul_f32_e32 v98, 0xbfb8aa3b, v130
	v_mul_f32_e32 v100, 0xbfb8aa3b, v131
	v_exp_f32_e32 v56, v56
	v_exp_f32_e32 v72, v72
	v_exp_f32_e32 v98, v98
	v_exp_f32_e32 v100, v100
	s_nop 0
	v_add_f32_e32 v56, 1.0, v56
	v_add_f32_e32 v72, 1.0, v72
	v_add_f32_e32 v98, 1.0, v98
	v_add_f32_e32 v100, 1.0, v100
	v_rcp_f32_e32 v56, v56
	v_rcp_f32_e32 v72, v72
	v_rcp_f32_e32 v98, v98
	v_rcp_f32_e32 v100, v100
	s_nop 0
	v_mul_f32_e32 v128, v128, v56
	v_mul_f32_e32 v129, v129, v72
	v_mul_f32_e32 v130, v130, v98
	v_mul_f32_e32 v131, v131, v100
	ds_write_b128 v33, v[128:131]
	s_waitcnt vmcnt(7)
	v_mul_f32_e32 v56, 0xbfb8aa3b, v132
	v_mul_f32_e32 v72, 0xbfb8aa3b, v133
	v_mul_f32_e32 v98, 0xbfb8aa3b, v134
	v_mul_f32_e32 v100, 0xbfb8aa3b, v135
	v_exp_f32_e32 v56, v56
	v_exp_f32_e32 v72, v72
	v_exp_f32_e32 v98, v98
	v_exp_f32_e32 v100, v100
	s_nop 0
	v_add_f32_e32 v56, 1.0, v56
	v_add_f32_e32 v72, 1.0, v72
	v_add_f32_e32 v98, 1.0, v98
	v_add_f32_e32 v100, 1.0, v100
	v_rcp_f32_e32 v56, v56
	v_rcp_f32_e32 v72, v72
	v_rcp_f32_e32 v98, v98
	v_rcp_f32_e32 v100, v100
	s_nop 0
	v_mul_f32_e32 v132, v132, v56
	v_mul_f32_e32 v133, v133, v72
	v_mul_f32_e32 v134, v134, v98
	v_mul_f32_e32 v135, v135, v100
	ds_write_b128 v33, v[132:135] offset:8224
	s_waitcnt vmcnt(6)
	v_mul_f32_e32 v56, 0xbfb8aa3b, v136
	v_mul_f32_e32 v72, 0xbfb8aa3b, v137
	v_mul_f32_e32 v98, 0xbfb8aa3b, v138
	v_mul_f32_e32 v100, 0xbfb8aa3b, v139
	v_exp_f32_e32 v56, v56
	v_exp_f32_e32 v72, v72
	v_exp_f32_e32 v98, v98
	v_exp_f32_e32 v100, v100
	s_nop 0
	v_add_f32_e32 v56, 1.0, v56
	v_add_f32_e32 v72, 1.0, v72
	v_add_f32_e32 v98, 1.0, v98
	v_add_f32_e32 v100, 1.0, v100
	v_rcp_f32_e32 v56, v56
	v_rcp_f32_e32 v72, v72
	v_rcp_f32_e32 v98, v98
	v_rcp_f32_e32 v100, v100
	s_nop 0
	v_mul_f32_e32 v136, v136, v56
	v_mul_f32_e32 v137, v137, v72
	v_mul_f32_e32 v138, v138, v98
	v_mul_f32_e32 v139, v139, v100
	ds_write_b128 v33, v[136:139] offset:16448
	s_waitcnt vmcnt(5)
	v_mul_f32_e32 v56, 0xbfb8aa3b, v148
	v_mul_f32_e32 v72, 0xbfb8aa3b, v149
	v_mul_f32_e32 v98, 0xbfb8aa3b, v150
	v_mul_f32_e32 v100, 0xbfb8aa3b, v151
	v_exp_f32_e32 v56, v56
	v_exp_f32_e32 v72, v72
	v_exp_f32_e32 v98, v98
	v_exp_f32_e32 v100, v100
	s_nop 0
	v_add_f32_e32 v56, 1.0, v56
	v_add_f32_e32 v72, 1.0, v72
	v_add_f32_e32 v98, 1.0, v98
	v_add_f32_e32 v100, 1.0, v100
	v_rcp_f32_e32 v56, v56
	v_rcp_f32_e32 v72, v72
	v_rcp_f32_e32 v98, v98
	v_rcp_f32_e32 v100, v100
	s_nop 0
	v_mul_f32_e32 v148, v148, v56
	v_mul_f32_e32 v149, v149, v72
	v_mul_f32_e32 v150, v150, v98
	v_mul_f32_e32 v151, v151, v100
	ds_write_b128 v33, v[148:151] offset:24672
	s_waitcnt vmcnt(4)
	v_mul_f32_e32 v56, 0xbfb8aa3b, v152
	v_mul_f32_e32 v72, 0xbfb8aa3b, v153
	v_mul_f32_e32 v98, 0xbfb8aa3b, v154
	v_mul_f32_e32 v100, 0xbfb8aa3b, v155
	v_exp_f32_e32 v56, v56
	v_exp_f32_e32 v72, v72
	v_exp_f32_e32 v98, v98
	v_exp_f32_e32 v100, v100
	s_nop 0
	v_add_f32_e32 v56, 1.0, v56
	v_add_f32_e32 v72, 1.0, v72
	v_add_f32_e32 v98, 1.0, v98
	v_add_f32_e32 v100, 1.0, v100
	v_rcp_f32_e32 v56, v56
	v_rcp_f32_e32 v72, v72
	v_rcp_f32_e32 v98, v98
	v_rcp_f32_e32 v100, v100
	s_nop 0
	v_mul_f32_e32 v152, v152, v56
	v_mul_f32_e32 v153, v153, v72
	v_mul_f32_e32 v154, v154, v98
	v_mul_f32_e32 v155, v155, v100
	ds_write_b128 v33, v[152:155] offset:32896
	s_waitcnt vmcnt(3)
	v_mul_f32_e32 v56, 0xbfb8aa3b, v164
	v_mul_f32_e32 v72, 0xbfb8aa3b, v165
	v_mul_f32_e32 v98, 0xbfb8aa3b, v166
	v_mul_f32_e32 v100, 0xbfb8aa3b, v167
	v_exp_f32_e32 v56, v56
	v_exp_f32_e32 v72, v72
	v_exp_f32_e32 v98, v98
	v_exp_f32_e32 v100, v100
	s_nop 0
	v_add_f32_e32 v56, 1.0, v56
	v_add_f32_e32 v72, 1.0, v72
	v_add_f32_e32 v98, 1.0, v98
	v_add_f32_e32 v100, 1.0, v100
	v_rcp_f32_e32 v56, v56
	v_rcp_f32_e32 v72, v72
	v_rcp_f32_e32 v98, v98
	v_rcp_f32_e32 v100, v100
	s_nop 0
	v_mul_f32_e32 v164, v164, v56
	v_mul_f32_e32 v165, v165, v72
	v_mul_f32_e32 v166, v166, v98
	v_mul_f32_e32 v167, v167, v100
	ds_write_b128 v33, v[164:167] offset:41120
	s_waitcnt vmcnt(2)
	v_mul_f32_e32 v56, 0xbfb8aa3b, v168
	v_mul_f32_e32 v72, 0xbfb8aa3b, v169
	v_mul_f32_e32 v98, 0xbfb8aa3b, v170
	v_mul_f32_e32 v100, 0xbfb8aa3b, v171
	v_exp_f32_e32 v56, v56
	v_exp_f32_e32 v72, v72
	v_exp_f32_e32 v98, v98
	v_exp_f32_e32 v100, v100
	s_nop 0
	v_add_f32_e32 v56, 1.0, v56
	v_add_f32_e32 v72, 1.0, v72
	v_add_f32_e32 v98, 1.0, v98
	v_add_f32_e32 v100, 1.0, v100
	v_rcp_f32_e32 v56, v56
	v_rcp_f32_e32 v72, v72
	v_rcp_f32_e32 v98, v98
	v_rcp_f32_e32 v100, v100
	s_nop 0
	v_mul_f32_e32 v168, v168, v56
	v_mul_f32_e32 v169, v169, v72
	v_mul_f32_e32 v170, v170, v98
	v_mul_f32_e32 v171, v171, v100
	ds_write_b128 v33, v[168:171] offset:49344
	s_waitcnt vmcnt(1)
	v_mul_f32_e32 v56, 0xbfb8aa3b, v176
	v_mul_f32_e32 v72, 0xbfb8aa3b, v177
	v_mul_f32_e32 v98, 0xbfb8aa3b, v178
	v_mul_f32_e32 v100, 0xbfb8aa3b, v179
	v_exp_f32_e32 v56, v56
	v_exp_f32_e32 v72, v72
	v_exp_f32_e32 v98, v98
	v_exp_f32_e32 v100, v100
	s_nop 0
	v_add_f32_e32 v56, 1.0, v56
	v_add_f32_e32 v72, 1.0, v72
	v_add_f32_e32 v98, 1.0, v98
	v_add_f32_e32 v100, 1.0, v100
	v_rcp_f32_e32 v56, v56
	v_rcp_f32_e32 v72, v72
	v_rcp_f32_e32 v98, v98
	v_rcp_f32_e32 v100, v100
	s_nop 0
	v_mul_f32_e32 v176, v176, v56
	v_mul_f32_e32 v177, v177, v72
	v_mul_f32_e32 v178, v178, v98
	v_mul_f32_e32 v179, v179, v100
	ds_write_b128 v33, v[176:179] offset:57568
	s_waitcnt vmcnt(0)
	v_readfirstlane_b32 s0, v224
	s_cmpk_lt_u32 s0, 0x100
	s_cbranch_scc0 .Lsilu_done
	v_mul_f32_e32 v56, 0xbfb8aa3b, v180
	v_mul_f32_e32 v72, 0xbfb8aa3b, v181
	v_mul_f32_e32 v98, 0xbfb8aa3b, v182
	v_mul_f32_e32 v100, 0xbfb8aa3b, v183
	v_exp_f32_e32 v56, v56
	v_exp_f32_e32 v72, v72
	v_exp_f32_e32 v98, v98
	v_exp_f32_e32 v100, v100
	s_nop 0
	v_add_f32_e32 v56, 1.0, v56
	v_add_f32_e32 v72, 1.0, v72
	v_add_f32_e32 v98, 1.0, v98
	v_add_f32_e32 v100, 1.0, v100
	v_rcp_f32_e32 v56, v56
	v_rcp_f32_e32 v72, v72
	v_rcp_f32_e32 v98, v98
	v_rcp_f32_e32 v100, v100
	s_nop 0
	v_mul_f32_e32 v180, v180, v56
	v_mul_f32_e32 v181, v181, v72
	v_mul_f32_e32 v182, v182, v98
	v_mul_f32_e32 v183, v183, v100
	ds_write_b128 v35, v[180:183]
.Lsilu_done:
.LBB0_49:
	s_or_b64 exec, exec, s[8:9]
	s_mul_hi_i32 s0, s2, 0x2aaaaaab
	s_mov_b64 s[4:5], s[78:79]
	s_waitcnt lgkmcnt(0)
	s_barrier
	s_lshr_b32 s1, s0, 31
	s_ashr_i32 s0, s0, 4
	s_ashr_i32 s6, s3, 6
	s_add_i32 s3, s0, s1
	s_load_dwordx2 s[4:5], s[4:5], 0x20
	s_mul_i32 s0, s3, 0x60
	s_sub_i32 s0, s2, s0
	s_lshl_b32 s0, s0, 6
	s_mul_i32 s15, s3, 0x1800000
	s_ashr_i32 s1, s0, 31
	s_mul_hi_i32 s14, s3, 0x1800000
	s_waitcnt lgkmcnt(0)
	s_add_u32 s7, s4, s15
	s_addc_u32 s9, s5, s14
	s_lshl_b64 s[12:13], s[0:1], 2
	v_and_b32_e32 v2, 31, v1
	s_add_u32 s8, s7, s12
	s_addc_u32 s9, s9, s13
	s_lshl_b32 s16, s6, 7
	v_lshlrev_b32_e32 v36, 2, v2
	v_mov_b32_e32 v37, 0
	v_lshl_add_u64 v[38:39], s[8:9], 0, v[36:37]
	s_or_b32 s1, s16, 0x70
	s_add_i32 s7, s16, -16
	s_mul_i32 s9, s6, 0x300000
	s_mul_hi_i32 s16, s16, 0x6000
	s_add_u32 s9, s15, s9
	s_addc_u32 s14, s14, s16
	s_add_u32 s9, s9, s12
	s_addc_u32 s12, s14, s13
	s_add_u32 s4, s4, s9
	v_mul_u32_u24_e32 v4, 0x1010, v2
	v_lshlrev_b32_e32 v2, 2, v34
	v_mov_b32_e32 v3, v37
	s_addc_u32 s5, s5, s12
	v_lshl_add_u64 v[2:3], s[4:5], 0, v[2:3]
	s_mov_b64 s[4:5], 0x5a000
	v_lshrrev_b32_e32 v35, 5, v34
	v_lshl_add_u64 v[40:41], v[2:3], 0, s[4:5]
	s_lshl_b32 s4, s6, 9
	s_add_i32 s4, s4, 0
	v_lshlrev_b32_e32 v46, 2, v35
	s_movk_i32 s8, 0x6000
	s_add_i32 s9, s4, 0x20200
	v_or_b32_e32 v47, v4, v46
	s_mov_b32 s12, 0xfffa6000
	s_mov_b32 s13, 0xfffac000
	s_mov_b32 s14, 0xfffb2000
	s_mov_b32 s15, 0xfffb8000
	s_mov_b32 s16, 0xfffbe000
	s_mov_b32 s17, 0xfffc4000
	s_mov_b32 s18, 0xfffca000
	s_mov_b32 s19, 0xfffd0000
	s_mov_b32 s20, 0xfffd6000
	s_mov_b32 s21, 0xfffdc000
	s_mov_b32 s22, 0xfffe2000
	s_mov_b32 s23, 0xfffe8000
	s_mov_b32 s24, 0xfffee000
	s_mov_b32 s25, 0xffff4000
	s_movk_i32 s26, 0xa000
	s_mov_b64 s[4:5], 0x60000
	v_mov_b32_e32 v2, v37
	v_mov_b32_e32 v3, v37
	v_mov_b32_e32 v4, v37
	v_mov_b32_e32 v5, v37
	v_mov_b32_e32 v6, v37
	v_mov_b32_e32 v7, v37
	v_mov_b32_e32 v8, v37
	v_mov_b32_e32 v9, v37
	v_mov_b32_e32 v10, v37
	v_mov_b32_e32 v11, v37
	v_mov_b32_e32 v12, v37
	v_mov_b32_e32 v13, v37
	v_mov_b32_e32 v14, v37
	v_mov_b32_e32 v15, v37
	v_mov_b32_e32 v16, v37
	v_mov_b32_e32 v17, v37
	v_mov_b32_e32 v18, v37
	v_mov_b32_e32 v19, v37
	v_mov_b32_e32 v20, v37
	v_mov_b32_e32 v21, v37
	v_mov_b32_e32 v22, v37
	v_mov_b32_e32 v23, v37
	v_mov_b32_e32 v24, v37
	v_mov_b32_e32 v25, v37
	v_mov_b32_e32 v26, v37
	v_mov_b32_e32 v27, v37
	v_mov_b32_e32 v28, v37
	v_mov_b32_e32 v29, v37
	v_mov_b32_e32 v30, v37
	v_mov_b32_e32 v31, v37
	v_mov_b32_e32 v32, v37
	v_mov_b32_e32 v33, v37
